# c40: output-GEMM epilogue loads the gate vector once per tile and batches the residual loads with counted waits
# baseline (speedup 1.0000x reference)
; template <bool LOWREG = false>
; __device__ __forceinline__ void gemm_core(const bf16_t* __restrict__ A, int lda, const bf16_t* __restrict__ Bt, int ldb, int K, f32x4 (&acc)[8][4], unsigned char* smem, int tid) {
;     ...
;     for (int kt = 0; kt < nk; ++kt) {
;         const int st = kt & 1;
;         const bool more = kt + 1 < nk;
;         const unsigned char* sb = smem + st * G_STAGE;
;         if constexpr (!LOWREG) {
; #pragma unroll
;         for (int ks = 0; ks < 2; ++ks) {
;             bf16x8 bfr[4], af[8];
;             const int co = ((ks * 4 + kq) ^ swz) * 16;
; #pragma unroll
;             for (int ni = 0; ni < 4; ++ni) bfr[ni] = *(const bf16x8*)(sb + boff + ni * 2048 + co);
; #pragma unroll
;             for (int mi = 0; mi < 8; ++mi) af[mi] = *(const bf16x8*)(sb + aoff + mi * 2048 + co);
;             if (more) { G_ISSUE1(kt + 1, st ^ 1, ks * 2); G_ISSUE1(kt + 1, st ^ 1, ks * 2 + 1); }
;             __builtin_amdgcn_sched_barrier(0);
;             __builtin_amdgcn_s_setprio(1);
; #pragma unroll
;             for (int mi = 0; mi < 8; ++mi)
; #pragma unroll
;                 for (int ni = 0; ni < 4; ++ni) acc[mi][ni] = __builtin_amdgcn_mfma_f32_16x16x32_bf16(bfr[ni], af[mi], acc[mi][ni], 0, 0, 0);
;             __builtin_amdgcn_s_setprio(0);
;             __builtin_amdgcn_sched_barrier(0);
;         }
;         } else {
; #pragma unroll
;         for (int ks = 0; ks < 2; ++ks) {
;             bf16x8 bfr[4];
;             const int co = ((ks * 4 + kq) ^ swz) * 16;
; #pragma unroll
;             for (int ni = 0; ni < 4; ++ni) bfr[ni] = *(const bf16x8*)(sb + boff + ni * 2048 + co);
; #pragma unroll
;             for (int mh = 0; mh < 2; ++mh) {
;                 bf16x8 af[4];
; #pragma unroll
;                 for (int mi = 0; mi < 4; ++mi) af[mi] = *(const bf16x8*)(sb + aoff + (mh * 4 + mi) * 2048 + co);
;                 if (more) G_ISSUE1(kt + 1, st ^ 1, ks * 2 + mh);
;                 __builtin_amdgcn_sched_barrier(0);
;                 __builtin_amdgcn_s_setprio(1);
; #pragma unroll
;                 for (int mi = 0; mi < 4; ++mi)
; #pragma unroll
;                     for (int ni = 0; ni < 4; ++ni) acc[mh * 4 + mi][ni] = __builtin_amdgcn_mfma_f32_16x16x32_bf16(bfr[ni], af[mi], acc[mh * 4 + mi][ni], 0, 0, 0);
;                 __builtin_amdgcn_s_setprio(0);
;                 __builtin_amdgcn_sched_barrier(0);
;             }
;         }
.LBB0_1286:
	s_and_b32 s27, s26, 0x10000
	s_add_i32 s28, s27, 0
	s_xor_b32 s27, s27, 0x10000
	v_add_u32_e32 v80, s28, v147
	v_add_u32_e32 v179, s28, v149
	s_add_i32 s27, s25, s27
	v_add_u32_e32 v162, v80, v148
	v_add_u32_e32 v196, v179, v148
	v_lshl_add_u64 v[200:201], v[130:131], 0, s[44:45]
	s_mov_b32 m0, s27
	ds_read_b128 v[150:153], v162 offset:32768
	ds_read_b128 v[154:157], v162 offset:34816
	ds_read_b128 v[158:161], v162 offset:36864
	ds_read_b128 v[162:165], v162 offset:38912
	ds_read_b128 v[166:169], v196
	ds_read_b128 v[170:173], v196 offset:2048
	ds_read_b128 v[174:177], v196 offset:4096
	ds_read_b128 v[180:183], v196 offset:6144
	ds_read_b128 v[184:187], v196 offset:8192
	ds_read_b128 v[188:191], v196 offset:10240
	ds_read_b128 v[192:195], v196 offset:12288
	ds_read_b128 v[196:199], v196 offset:14336
	global_load_lds_dwordx4 v[200:201], off
	v_lshl_add_u64 v[200:201], v[138:139], 0, s[44:45]
	s_add_i32 m0, s27, 0x8000
	s_nop 0
	global_load_lds_dwordx4 v[200:201], off
	v_lshl_add_u64 v[200:201], v[132:133], 0, s[44:45]
	s_add_i32 m0, s27, 0x2000
	s_nop 0
	global_load_lds_dwordx4 v[200:201], off
	v_lshl_add_u64 v[200:201], v[140:141], 0, s[44:45]
	s_add_i32 m0, s27, 0xa000
	s_nop 0
	global_load_lds_dwordx4 v[200:201], off
	s_setprio 1
	s_waitcnt lgkmcnt(0)
	v_mfma_f32_16x16x32_bf16 v[126:129], v[150:153], v[166:169], v[126:129]
	v_mfma_f32_16x16x32_bf16 v[122:125], v[154:157], v[166:169], v[122:125]
	v_mfma_f32_16x16x32_bf16 v[118:121], v[158:161], v[166:169], v[118:121]
	v_mfma_f32_16x16x32_bf16 v[114:117], v[162:165], v[166:169], v[114:117]
	v_mfma_f32_16x16x32_bf16 v[110:113], v[150:153], v[170:173], v[110:113]
	v_mfma_f32_16x16x32_bf16 v[106:109], v[154:157], v[170:173], v[106:109]
	v_mfma_f32_16x16x32_bf16 v[102:105], v[158:161], v[170:173], v[102:105]
	v_mfma_f32_16x16x32_bf16 v[98:101], v[162:165], v[170:173], v[98:101]
	v_mfma_f32_16x16x32_bf16 v[94:97], v[150:153], v[174:177], v[94:97]
	v_mfma_f32_16x16x32_bf16 v[90:93], v[154:157], v[174:177], v[90:93]
	v_mfma_f32_16x16x32_bf16 v[86:89], v[158:161], v[174:177], v[86:89]
	v_mfma_f32_16x16x32_bf16 v[82:85], v[162:165], v[174:177], v[82:85]
	v_mfma_f32_16x16x32_bf16 v[76:79], v[150:153], v[180:183], v[76:79]
	v_mfma_f32_16x16x32_bf16 v[72:75], v[154:157], v[180:183], v[72:75]
	v_mfma_f32_16x16x32_bf16 v[68:71], v[158:161], v[180:183], v[68:71]
	v_mfma_f32_16x16x32_bf16 v[64:67], v[162:165], v[180:183], v[64:67]
	v_mfma_f32_16x16x32_bf16 v[60:63], v[150:153], v[184:187], v[60:63]
	v_mfma_f32_16x16x32_bf16 v[56:59], v[154:157], v[184:187], v[56:59]
	v_mfma_f32_16x16x32_bf16 v[52:55], v[158:161], v[184:187], v[52:55]
	v_mfma_f32_16x16x32_bf16 v[48:51], v[162:165], v[184:187], v[48:51]
	v_mfma_f32_16x16x32_bf16 v[44:47], v[150:153], v[188:191], v[44:47]
	v_mfma_f32_16x16x32_bf16 v[40:43], v[154:157], v[188:191], v[40:43]
	v_mfma_f32_16x16x32_bf16 v[36:39], v[158:161], v[188:191], v[36:39]
	v_mfma_f32_16x16x32_bf16 v[32:35], v[162:165], v[188:191], v[32:35]
	v_mfma_f32_16x16x32_bf16 v[28:31], v[150:153], v[192:195], v[28:31]
	v_mfma_f32_16x16x32_bf16 v[24:27], v[154:157], v[192:195], v[24:27]
	v_mfma_f32_16x16x32_bf16 v[20:23], v[158:161], v[192:195], v[20:23]
	v_mfma_f32_16x16x32_bf16 v[16:19], v[162:165], v[192:195], v[16:19]
	v_mfma_f32_16x16x32_bf16 v[12:15], v[150:153], v[196:199], v[12:15]
	v_mfma_f32_16x16x32_bf16 v[8:11], v[154:157], v[196:199], v[8:11]
	v_mfma_f32_16x16x32_bf16 v[4:7], v[158:161], v[196:199], v[4:7]
	v_mfma_f32_16x16x32_bf16 v[0:3], v[162:165], v[196:199], v[0:3]
	s_setprio 0
	v_add_u32_e32 v80, v80, v146
	ds_read_b128 v[150:153], v80 offset:32768
	ds_read_b128 v[154:157], v80 offset:34816
	ds_read_b128 v[158:161], v80 offset:36864
	ds_read_b128 v[162:165], v80 offset:38912
	v_add_u32_e32 v80, v179, v146
	v_lshl_add_u64 v[200:201], v[134:135], 0, s[44:45]
	s_add_i32 m0, s27, 0x4000
	ds_read_b128 v[166:169], v80
	ds_read_b128 v[170:173], v80 offset:2048
	ds_read_b128 v[174:177], v80 offset:4096
	ds_read_b128 v[180:183], v80 offset:6144
	ds_read_b128 v[184:187], v80 offset:8192
	ds_read_b128 v[188:191], v80 offset:10240
	ds_read_b128 v[192:195], v80 offset:12288
	ds_read_b128 v[196:199], v80 offset:14336
	global_load_lds_dwordx4 v[200:201], off
	v_lshl_add_u64 v[200:201], v[142:143], 0, s[44:45]
	s_add_i32 m0, s27, 0xc000
	s_nop 0
	global_load_lds_dwordx4 v[200:201], off
	v_lshl_add_u64 v[200:201], v[136:137], 0, s[44:45]
	s_add_i32 m0, s27, 0x6000
	s_nop 0
	global_load_lds_dwordx4 v[200:201], off
	v_lshl_add_u64 v[200:201], v[144:145], 0, s[44:45]
	s_add_i32 m0, s27, 0xe000
	s_nop 0
	global_load_lds_dwordx4 v[200:201], off
	s_setprio 1
	s_waitcnt lgkmcnt(0)
	v_mfma_f32_16x16x32_bf16 v[126:129], v[150:153], v[166:169], v[126:129]
	v_mfma_f32_16x16x32_bf16 v[122:125], v[154:157], v[166:169], v[122:125]
	v_mfma_f32_16x16x32_bf16 v[118:121], v[158:161], v[166:169], v[118:121]
	v_mfma_f32_16x16x32_bf16 v[114:117], v[162:165], v[166:169], v[114:117]
	v_mfma_f32_16x16x32_bf16 v[110:113], v[150:153], v[170:173], v[110:113]
	v_mfma_f32_16x16x32_bf16 v[106:109], v[154:157], v[170:173], v[106:109]
	v_mfma_f32_16x16x32_bf16 v[102:105], v[158:161], v[170:173], v[102:105]
	v_mfma_f32_16x16x32_bf16 v[98:101], v[162:165], v[170:173], v[98:101]
	v_mfma_f32_16x16x32_bf16 v[94:97], v[150:153], v[174:177], v[94:97]
	v_mfma_f32_16x16x32_bf16 v[90:93], v[154:157], v[174:177], v[90:93]
	v_mfma_f32_16x16x32_bf16 v[86:89], v[158:161], v[174:177], v[86:89]
	v_mfma_f32_16x16x32_bf16 v[82:85], v[162:165], v[174:177], v[82:85]
	v_mfma_f32_16x16x32_bf16 v[76:79], v[150:153], v[180:183], v[76:79]
	v_mfma_f32_16x16x32_bf16 v[72:75], v[154:157], v[180:183], v[72:75]
	v_mfma_f32_16x16x32_bf16 v[68:71], v[158:161], v[180:183], v[68:71]
	v_mfma_f32_16x16x32_bf16 v[64:67], v[162:165], v[180:183], v[64:67]
	v_mfma_f32_16x16x32_bf16 v[60:63], v[150:153], v[184:187], v[60:63]
	v_mfma_f32_16x16x32_bf16 v[56:59], v[154:157], v[184:187], v[56:59]
	v_mfma_f32_16x16x32_bf16 v[52:55], v[158:161], v[184:187], v[52:55]
	v_mfma_f32_16x16x32_bf16 v[48:51], v[162:165], v[184:187], v[48:51]
	v_mfma_f32_16x16x32_bf16 v[44:47], v[150:153], v[188:191], v[44:47]
	v_mfma_f32_16x16x32_bf16 v[40:43], v[154:157], v[188:191], v[40:43]
	v_mfma_f32_16x16x32_bf16 v[36:39], v[158:161], v[188:191], v[36:39]
	v_mfma_f32_16x16x32_bf16 v[32:35], v[162:165], v[188:191], v[32:35]
	v_mfma_f32_16x16x32_bf16 v[28:31], v[150:153], v[192:195], v[28:31]
	v_mfma_f32_16x16x32_bf16 v[24:27], v[154:157], v[192:195], v[24:27]
	v_mfma_f32_16x16x32_bf16 v[20:23], v[158:161], v[192:195], v[20:23]
	v_mfma_f32_16x16x32_bf16 v[16:19], v[162:165], v[192:195], v[16:19]
	v_mfma_f32_16x16x32_bf16 v[12:15], v[150:153], v[196:199], v[12:15]
	v_mfma_f32_16x16x32_bf16 v[8:11], v[154:157], v[196:199], v[8:11]
	v_mfma_f32_16x16x32_bf16 v[4:7], v[158:161], v[196:199], v[4:7]
	v_mfma_f32_16x16x32_bf16 v[0:3], v[162:165], v[196:199], v[0:3]
	s_setprio 0
	s_add_i32 s26, s26, 0x10000
	s_waitcnt vmcnt(0)
	s_add_u32 s44, s44, 0x80
	s_addc_u32 s45, s45, 0
	s_cmpk_lg_i32 s44, 0x780
	s_waitcnt vmcnt(0)
	s_barrier
; template <bool LOWREG = false>
; __device__ __forceinline__ void gemm_core(const bf16_t* __restrict__ A, int lda, const bf16_t* __restrict__ Bt, int ldb, int K, f32x4 (&acc)[8][4], unsigned char* smem, int tid) {
;     ...
;     for (int kt = 0; kt < nk; ++kt) {
;         const int st = kt & 1;
;         const bool more = kt + 1 < nk;
;         const unsigned char* sb = smem + st * G_STAGE;
;         if constexpr (!LOWREG) {
; #pragma unroll
;         for (int ks = 0; ks < 2; ++ks) {
;             bf16x8 bfr[4], af[8];
;             const int co = ((ks * 4 + kq) ^ swz) * 16;
; #pragma unroll
;             for (int ni = 0; ni < 4; ++ni) bfr[ni] = *(const bf16x8*)(sb + boff + ni * 2048 + co);
; #pragma unroll
;             for (int mi = 0; mi < 8; ++mi) af[mi] = *(const bf16x8*)(sb + aoff + mi * 2048 + co);
;             if (more) { G_ISSUE1(kt + 1, st ^ 1, ks * 2); G_ISSUE1(kt + 1, st ^ 1, ks * 2 + 1); }
;             __builtin_amdgcn_sched_barrier(0);
;             __builtin_amdgcn_s_setprio(1);
; #pragma unroll
;             for (int mi = 0; mi < 8; ++mi)
; #pragma unroll
;                 for (int ni = 0; ni < 4; ++ni) acc[mi][ni] = __builtin_amdgcn_mfma_f32_16x16x32_bf16(bfr[ni], af[mi], acc[mi][ni], 0, 0, 0);
;             __builtin_amdgcn_s_setprio(0);
;             __builtin_amdgcn_sched_barrier(0);
;         }
;         } else {
; #pragma unroll
;         for (int ks = 0; ks < 2; ++ks) {
;             bf16x8 bfr[4];
;             const int co = ((ks * 4 + kq) ^ swz) * 16;
; #pragma unroll
;             for (int ni = 0; ni < 4; ++ni) bfr[ni] = *(const bf16x8*)(sb + boff + ni * 2048 + co);
; #pragma unroll
;             for (int mh = 0; mh < 2; ++mh) {
;                 bf16x8 af[4];
; #pragma unroll
;                 for (int mi = 0; mi < 4; ++mi) af[mi] = *(const bf16x8*)(sb + aoff + (mh * 4 + mi) * 2048 + co);
;                 if (more) G_ISSUE1(kt + 1, st ^ 1, ks * 2 + mh);
;                 __builtin_amdgcn_sched_barrier(0);
;                 __builtin_amdgcn_s_setprio(1);
; #pragma unroll
;                 for (int mi = 0; mi < 4; ++mi)
; #pragma unroll
;                     for (int ni = 0; ni < 4; ++ni) acc[mh * 4 + mi][ni] = __builtin_amdgcn_mfma_f32_16x16x32_bf16(bfr[ni], af[mi], acc[mh * 4 + mi][ni], 0, 0, 0);
;                 __builtin_amdgcn_s_setprio(0);
;                 __builtin_amdgcn_sched_barrier(0);
;             }
;         }
	s_cbranch_scc1 .LBB0_1286
	s_add_i32 s25, 0, 0x10000
	v_add_u32_e32 v80, s25, v149
	v_add_u32_e32 v149, v80, v148
	ds_read_b128 v[130:133], v149 offset:14336
	ds_read_b128 v[134:137], v149 offset:12288
	ds_read_b128 v[138:141], v149 offset:10240
	ds_read_b128 v[142:145], v149 offset:8192
	ds_read_b128 v[150:153], v149 offset:6144
	ds_read_b128 v[154:157], v149 offset:4096
	ds_read_b128 v[158:161], v149 offset:2048
	ds_read_b128 v[162:165], v149
	v_add_u32_e32 v147, s25, v147
	v_add_u32_e32 v148, v147, v148
	ds_read_b128 v[166:169], v148 offset:38912
	ds_read_b128 v[170:173], v148 offset:36864
	ds_read_b128 v[174:177], v148 offset:34816
	ds_read_b128 v[180:183], v148 offset:32768
	s_setprio 1
	s_waitcnt lgkmcnt(0)
	v_mfma_f32_16x16x32_bf16 v[126:129], v[180:183], v[162:165], v[126:129]
	v_mfma_f32_16x16x32_bf16 v[122:125], v[174:177], v[162:165], v[122:125]
	v_mfma_f32_16x16x32_bf16 v[118:121], v[170:173], v[162:165], v[118:121]
	v_mfma_f32_16x16x32_bf16 v[114:117], v[166:169], v[162:165], v[114:117]
	v_mfma_f32_16x16x32_bf16 v[110:113], v[180:183], v[158:161], v[110:113]
	v_mfma_f32_16x16x32_bf16 v[106:109], v[174:177], v[158:161], v[106:109]
	v_mfma_f32_16x16x32_bf16 v[102:105], v[170:173], v[158:161], v[102:105]
	v_mfma_f32_16x16x32_bf16 v[98:101], v[166:169], v[158:161], v[98:101]
	v_mfma_f32_16x16x32_bf16 v[94:97], v[180:183], v[154:157], v[94:97]
	v_mfma_f32_16x16x32_bf16 v[90:93], v[174:177], v[154:157], v[90:93]
	v_mfma_f32_16x16x32_bf16 v[86:89], v[170:173], v[154:157], v[86:89]
	v_mfma_f32_16x16x32_bf16 v[82:85], v[166:169], v[154:157], v[82:85]
	v_mfma_f32_16x16x32_bf16 v[76:79], v[180:183], v[150:153], v[76:79]
	v_mfma_f32_16x16x32_bf16 v[72:75], v[174:177], v[150:153], v[72:75]
	v_mfma_f32_16x16x32_bf16 v[68:71], v[170:173], v[150:153], v[68:71]
	v_mfma_f32_16x16x32_bf16 v[64:67], v[166:169], v[150:153], v[64:67]
	v_mfma_f32_16x16x32_bf16 v[60:63], v[180:183], v[142:145], v[60:63]
	v_mfma_f32_16x16x32_bf16 v[56:59], v[174:177], v[142:145], v[56:59]
	v_mfma_f32_16x16x32_bf16 v[52:55], v[170:173], v[142:145], v[52:55]
	v_mfma_f32_16x16x32_bf16 v[48:51], v[166:169], v[142:145], v[48:51]
	v_mfma_f32_16x16x32_bf16 v[44:47], v[180:183], v[138:141], v[44:47]
	v_mfma_f32_16x16x32_bf16 v[40:43], v[174:177], v[138:141], v[40:43]
	v_mfma_f32_16x16x32_bf16 v[36:39], v[170:173], v[138:141], v[36:39]
	v_mfma_f32_16x16x32_bf16 v[32:35], v[166:169], v[138:141], v[32:35]
	v_mfma_f32_16x16x32_bf16 v[28:31], v[180:183], v[134:137], v[28:31]
	v_mfma_f32_16x16x32_bf16 v[24:27], v[174:177], v[134:137], v[24:27]
	v_mfma_f32_16x16x32_bf16 v[20:23], v[170:173], v[134:137], v[20:23]
	v_mfma_f32_16x16x32_bf16 v[16:19], v[166:169], v[134:137], v[16:19]
	v_mfma_f32_16x16x32_bf16 v[12:15], v[180:183], v[130:133], v[12:15]
	v_mfma_f32_16x16x32_bf16 v[8:11], v[174:177], v[130:133], v[8:11]
	v_mfma_f32_16x16x32_bf16 v[4:7], v[170:173], v[130:133], v[4:7]
	v_mfma_f32_16x16x32_bf16 v[0:3], v[166:169], v[130:133], v[0:3]
	s_setprio 0
	v_add_u32_e32 v80, v80, v146
	ds_read_b128 v[130:133], v80 offset:14336
	ds_read_b128 v[134:137], v80 offset:12288
	ds_read_b128 v[138:141], v80 offset:10240
	ds_read_b128 v[142:145], v80 offset:8192
	ds_read_b128 v[148:151], v80 offset:6144
	ds_read_b128 v[152:155], v80 offset:4096
	ds_read_b128 v[156:159], v80 offset:2048
	ds_read_b128 v[160:163], v80
	v_add_u32_e32 v80, v147, v146
	ds_read_b128 v[164:167], v80 offset:38912
	ds_read_b128 v[168:171], v80 offset:36864
	ds_read_b128 v[172:175], v80 offset:34816
	ds_read_b128 v[180:183], v80 offset:32768
	s_setprio 1
	s_waitcnt lgkmcnt(0)
	v_mfma_f32_16x16x32_bf16 v[184:187], v[180:183], v[160:163], v[126:129]
	v_mfma_f32_16x16x32_bf16 v[188:191], v[172:175], v[160:163], v[122:125]
	v_mfma_f32_16x16x32_bf16 v[192:195], v[168:171], v[160:163], v[118:121]
	v_mfma_f32_16x16x32_bf16 v[114:117], v[164:167], v[160:163], v[114:117]
	v_mfma_f32_16x16x32_bf16 v[110:113], v[180:183], v[156:159], v[110:113]
	v_mfma_f32_16x16x32_bf16 v[106:109], v[172:175], v[156:159], v[106:109]
	v_mfma_f32_16x16x32_bf16 v[102:105], v[168:171], v[156:159], v[102:105]
	v_mfma_f32_16x16x32_bf16 v[98:101], v[164:167], v[156:159], v[98:101]
	v_mfma_f32_16x16x32_bf16 v[94:97], v[180:183], v[152:155], v[94:97]
	v_mfma_f32_16x16x32_bf16 v[90:93], v[172:175], v[152:155], v[90:93]
	v_mfma_f32_16x16x32_bf16 v[86:89], v[168:171], v[152:155], v[86:89]
	v_mfma_f32_16x16x32_bf16 v[82:85], v[164:167], v[152:155], v[82:85]
	v_mfma_f32_16x16x32_bf16 v[76:79], v[180:183], v[148:151], v[76:79]
	v_mfma_f32_16x16x32_bf16 v[72:75], v[172:175], v[148:151], v[72:75]
	v_mfma_f32_16x16x32_bf16 v[68:71], v[168:171], v[148:151], v[68:71]
	v_mfma_f32_16x16x32_bf16 v[64:67], v[164:167], v[148:151], v[64:67]
	v_mfma_f32_16x16x32_bf16 v[60:63], v[180:183], v[142:145], v[60:63]
	v_mfma_f32_16x16x32_bf16 v[56:59], v[172:175], v[142:145], v[56:59]
	v_mfma_f32_16x16x32_bf16 v[52:55], v[168:171], v[142:145], v[52:55]
	v_mfma_f32_16x16x32_bf16 v[48:51], v[164:167], v[142:145], v[48:51]
	v_mfma_f32_16x16x32_bf16 v[44:47], v[180:183], v[138:141], v[44:47]
	v_mfma_f32_16x16x32_bf16 v[40:43], v[172:175], v[138:141], v[40:43]
	v_mfma_f32_16x16x32_bf16 v[36:39], v[168:171], v[138:141], v[36:39]
	v_mfma_f32_16x16x32_bf16 v[32:35], v[164:167], v[138:141], v[32:35]
	v_mfma_f32_16x16x32_bf16 v[28:31], v[180:183], v[134:137], v[28:31]
	v_mfma_f32_16x16x32_bf16 v[24:27], v[172:175], v[134:137], v[24:27]
	v_mfma_f32_16x16x32_bf16 v[20:23], v[168:171], v[134:137], v[20:23]
	v_mfma_f32_16x16x32_bf16 v[16:19], v[164:167], v[134:137], v[16:19]
	v_mfma_f32_16x16x32_bf16 v[12:15], v[180:183], v[130:133], v[12:15]
	v_mfma_f32_16x16x32_bf16 v[8:11], v[172:175], v[130:133], v[8:11]
	v_mfma_f32_16x16x32_bf16 v[4:7], v[168:171], v[130:133], v[4:7]
	v_mfma_f32_16x16x32_bf16 v[0:3], v[164:167], v[130:133], v[0:3]
	s_setprio 0
	v_mov_b32_e32 v80, v210
	s_waitcnt vmcnt(0)
	s_barrier
; __device__ void out_phase(const Params& p, int l, int hb, const float* xsrc, unsigned char* smem) {
;     ...
; #pragma unroll
;         for (int mi = 0; mi < 8; ++mi) {
;             const int row = m0 + wm * 128 + mi * 16 + idx; const size_t rg = (size_t)hb * TP + row; const int b = (int)(rg / SEQ);
;             const float* gate = (const float*)(p.ws + WS_MOD) + (size_t)(l * 4 + b) * 3072 + 2048;
; #pragma unroll
;             for (int ni = 0; ni < 4; ++ni) {
;                 const int col = n0 + wn * 64 + ni * 16 + 4 * kq;
;                 const f32x4 xv = *(const f32x4*)(xsrc + rg * 1024 + col), gv = *(const f32x4*)(gate + col);
;                 *(f32x4*)(p.out + rg * 1024 + col) = xv + gv * acc[mi][ni];
;             }
;         }
	v_mov_b64_e32 v[126:127], s[40:41]
	v_ashrrev_i32_e32 v119, 1, v80
	v_and_b32_e32 v119, 0xffffff80, v119
	v_add_u32_e32 v119, s42, v119
	v_and_b32_e32 v118, 0xc0, v80
	v_and_or_b32 v124, v80, 15, v119
	v_lshrrev_b32_e32 v80, 2, v80
	v_and_b32_e32 v80, 12, v80
	v_ashrrev_i32_e32 v125, 31, v124
	v_or3_b32 v80, v118, v80, s24
	v_lshl_add_u64 v[118:119], s[86:87], 0, v[124:125]
	v_alignbit_b32 v120, v119, v118, 13
	v_add_u32_e32 v120, s10, v120
	v_mad_i64_i32 v[120:121], s[24:25], v120, s33, v[126:127]
	v_lshlrev_b64 v[118:119], 12, v[118:119]
	v_lshl_add_u64 v[136:137], v[120:121], 0, s[84:85]
	v_lshl_add_u64 v[120:121], s[36:37], 0, v[118:119]
	v_lshlrev_b32_e32 v80, 2, v80
	v_lshl_add_u64 v[138:139], v[120:121], 0, v[80:81]
	v_lshl_add_u64 v[128:129], v[136:137], 0, v[80:81]
	v_lshl_add_u64 v[122:123], s[38:39], 0, v[118:119]
	v_lshl_add_u64 v[140:141], v[122:123], 0, v[80:81]
	global_load_dwordx4 v[174:177], v[128:129], off
	global_load_dwordx4 v[178:181], v[128:129], off offset:64
	global_load_dwordx4 v[196:199], v[128:129], off offset:128
	global_load_dwordx4 v[132:135], v[128:129], off offset:192
	s_mov_b32 s100, 0x10000
	s_mov_b32 s101, 0
	global_load_dwordx4 v[142:145], v[138:139], off
	global_load_dwordx4 v[146:149], v[138:139], off offset:64
	global_load_dwordx4 v[150:153], v[138:139], off offset:128
	global_load_dwordx4 v[154:157], v[138:139], off offset:192
	v_lshl_add_u64 v[138:139], v[138:139], 0, s[100:101]
	global_load_dwordx4 v[158:161], v[138:139], off
	global_load_dwordx4 v[162:165], v[138:139], off offset:64
	global_load_dwordx4 v[166:169], v[138:139], off offset:128
	global_load_dwordx4 v[170:173], v[138:139], off offset:192
	v_lshl_add_u64 v[138:139], v[138:139], 0, s[100:101]
	s_waitcnt vmcnt(0)
	v_pk_fma_f32 v[184:185], v[184:185], v[174:175], v[142:143]
	v_pk_fma_f32 v[186:187], v[186:187], v[176:177], v[144:145]
	v_pk_fma_f32 v[188:189], v[188:189], v[178:179], v[146:147]
	v_pk_fma_f32 v[190:191], v[190:191], v[180:181], v[148:149]
	v_pk_fma_f32 v[192:193], v[192:193], v[196:197], v[150:151]
	v_pk_fma_f32 v[194:195], v[194:195], v[198:199], v[152:153]
	v_pk_fma_f32 v[114:115], v[114:115], v[132:133], v[154:155]
	v_pk_fma_f32 v[116:117], v[116:117], v[134:135], v[156:157]
	v_pk_fma_f32 v[110:111], v[110:111], v[174:175], v[158:159]
	v_pk_fma_f32 v[112:113], v[112:113], v[176:177], v[160:161]
	v_pk_fma_f32 v[106:107], v[106:107], v[178:179], v[162:163]
	v_pk_fma_f32 v[108:109], v[108:109], v[180:181], v[164:165]
	v_pk_fma_f32 v[102:103], v[102:103], v[196:197], v[166:167]
	v_pk_fma_f32 v[104:105], v[104:105], v[198:199], v[168:169]
	v_pk_fma_f32 v[98:99], v[98:99], v[132:133], v[170:171]
	v_pk_fma_f32 v[100:101], v[100:101], v[134:135], v[172:173]
	global_load_dwordx4 v[142:145], v[138:139], off
	global_load_dwordx4 v[146:149], v[138:139], off offset:64
	global_load_dwordx4 v[150:153], v[138:139], off offset:128
	global_load_dwordx4 v[154:157], v[138:139], off offset:192
	v_lshl_add_u64 v[138:139], v[138:139], 0, s[100:101]
	global_load_dwordx4 v[158:161], v[138:139], off
	global_load_dwordx4 v[162:165], v[138:139], off offset:64
	global_load_dwordx4 v[166:169], v[138:139], off offset:128
	global_load_dwordx4 v[170:173], v[138:139], off offset:192
	v_lshl_add_u64 v[138:139], v[138:139], 0, s[100:101]
	global_store_dwordx4 v[140:141], v[184:187], off
	global_store_dwordx4 v[140:141], v[188:191], off offset:64
	global_store_dwordx4 v[140:141], v[192:195], off offset:128
	global_store_dwordx4 v[140:141], v[114:117], off offset:192
	s_nop 1
	v_lshl_add_u64 v[140:141], v[140:141], 0, s[100:101]
	global_store_dwordx4 v[140:141], v[110:113], off
	global_store_dwordx4 v[140:141], v[106:109], off offset:64
	global_store_dwordx4 v[140:141], v[102:105], off offset:128
	global_store_dwordx4 v[140:141], v[98:101], off offset:192
	s_nop 1
	v_lshl_add_u64 v[140:141], v[140:141], 0, s[100:101]
	s_waitcnt vmcnt(8)
; __device__ void out_phase(const Params& p, int l, int hb, const float* xsrc, unsigned char* smem) {
;     ...
; #pragma unroll
;         for (int mi = 0; mi < 8; ++mi) {
;             const int row = m0 + wm * 128 + mi * 16 + idx; const size_t rg = (size_t)hb * TP + row; const int b = (int)(rg / SEQ);
;             const float* gate = (const float*)(p.ws + WS_MOD) + (size_t)(l * 4 + b) * 3072 + 2048;
; #pragma unroll
;             for (int ni = 0; ni < 4; ++ni) {
;                 const int col = n0 + wn * 64 + ni * 16 + 4 * kq;
;                 const f32x4 xv = *(const f32x4*)(xsrc + rg * 1024 + col), gv = *(const f32x4*)(gate + col);
;                 *(f32x4*)(p.out + rg * 1024 + col) = xv + gv * acc[mi][ni];
;             }
;         }
	v_pk_fma_f32 v[94:95], v[94:95], v[174:175], v[142:143]
	v_pk_fma_f32 v[96:97], v[96:97], v[176:177], v[144:145]
	v_pk_fma_f32 v[90:91], v[90:91], v[178:179], v[146:147]
	v_pk_fma_f32 v[92:93], v[92:93], v[180:181], v[148:149]
	v_pk_fma_f32 v[86:87], v[86:87], v[196:197], v[150:151]
	v_pk_fma_f32 v[88:89], v[88:89], v[198:199], v[152:153]
	v_pk_fma_f32 v[82:83], v[82:83], v[132:133], v[154:155]
	v_pk_fma_f32 v[84:85], v[84:85], v[134:135], v[156:157]
	v_pk_fma_f32 v[76:77], v[76:77], v[174:175], v[158:159]
	v_pk_fma_f32 v[78:79], v[78:79], v[176:177], v[160:161]
	v_pk_fma_f32 v[72:73], v[72:73], v[178:179], v[162:163]
	v_pk_fma_f32 v[74:75], v[74:75], v[180:181], v[164:165]
	v_pk_fma_f32 v[68:69], v[68:69], v[196:197], v[166:167]
	v_pk_fma_f32 v[70:71], v[70:71], v[198:199], v[168:169]
	v_pk_fma_f32 v[64:65], v[64:65], v[132:133], v[170:171]
	v_pk_fma_f32 v[66:67], v[66:67], v[134:135], v[172:173]
	global_load_dwordx4 v[142:145], v[138:139], off
	global_load_dwordx4 v[146:149], v[138:139], off offset:64
	global_load_dwordx4 v[150:153], v[138:139], off offset:128
	global_load_dwordx4 v[154:157], v[138:139], off offset:192
	v_lshl_add_u64 v[138:139], v[138:139], 0, s[100:101]
	global_load_dwordx4 v[158:161], v[138:139], off
	global_load_dwordx4 v[162:165], v[138:139], off offset:64
	global_load_dwordx4 v[166:169], v[138:139], off offset:128
	global_load_dwordx4 v[170:173], v[138:139], off offset:192
	v_lshl_add_u64 v[138:139], v[138:139], 0, s[100:101]
	global_store_dwordx4 v[140:141], v[94:97], off
	global_store_dwordx4 v[140:141], v[90:93], off offset:64
	global_store_dwordx4 v[140:141], v[86:89], off offset:128
	global_store_dwordx4 v[140:141], v[82:85], off offset:192
	s_nop 1
	v_lshl_add_u64 v[140:141], v[140:141], 0, s[100:101]
	global_store_dwordx4 v[140:141], v[76:79], off
	global_store_dwordx4 v[140:141], v[72:75], off offset:64
	global_store_dwordx4 v[140:141], v[68:71], off offset:128
	global_store_dwordx4 v[140:141], v[64:67], off offset:192
	s_nop 1
	v_lshl_add_u64 v[140:141], v[140:141], 0, s[100:101]
	s_waitcnt vmcnt(8)
	v_pk_fma_f32 v[60:61], v[60:61], v[174:175], v[142:143]
	v_pk_fma_f32 v[62:63], v[62:63], v[176:177], v[144:145]
	v_pk_fma_f32 v[56:57], v[56:57], v[178:179], v[146:147]
	v_pk_fma_f32 v[58:59], v[58:59], v[180:181], v[148:149]
	v_pk_fma_f32 v[52:53], v[52:53], v[196:197], v[150:151]
	v_pk_fma_f32 v[54:55], v[54:55], v[198:199], v[152:153]
	v_pk_fma_f32 v[48:49], v[48:49], v[132:133], v[154:155]
	v_pk_fma_f32 v[50:51], v[50:51], v[134:135], v[156:157]
	v_pk_fma_f32 v[44:45], v[44:45], v[174:175], v[158:159]
	v_pk_fma_f32 v[46:47], v[46:47], v[176:177], v[160:161]
	v_pk_fma_f32 v[40:41], v[40:41], v[178:179], v[162:163]
	v_pk_fma_f32 v[42:43], v[42:43], v[180:181], v[164:165]
	v_pk_fma_f32 v[36:37], v[36:37], v[196:197], v[166:167]
	v_pk_fma_f32 v[38:39], v[38:39], v[198:199], v[168:169]
	v_pk_fma_f32 v[32:33], v[32:33], v[132:133], v[170:171]
	v_pk_fma_f32 v[34:35], v[34:35], v[134:135], v[172:173]
	global_load_dwordx4 v[142:145], v[138:139], off
	global_load_dwordx4 v[146:149], v[138:139], off offset:64
	global_load_dwordx4 v[150:153], v[138:139], off offset:128
	global_load_dwordx4 v[154:157], v[138:139], off offset:192
	v_lshl_add_u64 v[138:139], v[138:139], 0, s[100:101]
	global_load_dwordx4 v[158:161], v[138:139], off
	global_load_dwordx4 v[162:165], v[138:139], off offset:64
	global_load_dwordx4 v[166:169], v[138:139], off offset:128
	global_load_dwordx4 v[170:173], v[138:139], off offset:192
	v_lshl_add_u64 v[138:139], v[138:139], 0, s[100:101]
	global_store_dwordx4 v[140:141], v[60:63], off
	global_store_dwordx4 v[140:141], v[56:59], off offset:64
	global_store_dwordx4 v[140:141], v[52:55], off offset:128
	global_store_dwordx4 v[140:141], v[48:51], off offset:192
	s_nop 1
	v_lshl_add_u64 v[140:141], v[140:141], 0, s[100:101]
	global_store_dwordx4 v[140:141], v[44:47], off
	global_store_dwordx4 v[140:141], v[40:43], off offset:64
	global_store_dwordx4 v[140:141], v[36:39], off offset:128
	global_store_dwordx4 v[140:141], v[32:35], off offset:192
	s_nop 1
	v_lshl_add_u64 v[140:141], v[140:141], 0, s[100:101]
	s_waitcnt vmcnt(8)
	v_pk_fma_f32 v[28:29], v[28:29], v[174:175], v[142:143]
	v_pk_fma_f32 v[30:31], v[30:31], v[176:177], v[144:145]
	v_pk_fma_f32 v[24:25], v[24:25], v[178:179], v[146:147]
	v_pk_fma_f32 v[26:27], v[26:27], v[180:181], v[148:149]
	v_pk_fma_f32 v[20:21], v[20:21], v[196:197], v[150:151]
	v_pk_fma_f32 v[22:23], v[22:23], v[198:199], v[152:153]
	v_pk_fma_f32 v[16:17], v[16:17], v[132:133], v[154:155]
	v_pk_fma_f32 v[18:19], v[18:19], v[134:135], v[156:157]
	v_pk_fma_f32 v[12:13], v[12:13], v[174:175], v[158:159]
	v_pk_fma_f32 v[14:15], v[14:15], v[176:177], v[160:161]
	v_pk_fma_f32 v[8:9], v[8:9], v[178:179], v[162:163]
	v_pk_fma_f32 v[10:11], v[10:11], v[180:181], v[164:165]
	v_pk_fma_f32 v[4:5], v[4:5], v[196:197], v[166:167]
	v_pk_fma_f32 v[6:7], v[6:7], v[198:199], v[168:169]
	v_pk_fma_f32 v[0:1], v[0:1], v[132:133], v[170:171]
	v_pk_fma_f32 v[2:3], v[2:3], v[134:135], v[172:173]
	global_store_dwordx4 v[140:141], v[28:31], off
	global_store_dwordx4 v[140:141], v[24:27], off offset:64
	global_store_dwordx4 v[140:141], v[20:23], off offset:128
	global_store_dwordx4 v[140:141], v[16:19], off offset:192
	s_nop 1
	v_lshl_add_u64 v[140:141], v[140:141], 0, s[100:101]
	global_store_dwordx4 v[140:141], v[12:15], off
	global_store_dwordx4 v[140:141], v[8:11], off offset:64
	global_store_dwordx4 v[140:141], v[4:7], off offset:128
	global_store_dwordx4 v[140:141], v[0:3], off offset:192
	s_nop 1
	v_lshl_add_u64 v[140:141], v[140:141], 0, s[100:101]
	s_add_i32 s23, s23, s8
	s_add_i32 s22, s22, s8
	s_add_i32 s21, s21, s6
	s_cmpk_lt_i32 s23, 0x100
	s_cbranch_scc1 .LBB0_1285
	s_mov_b32 s12, 0x3000000
	s_branch .LBB0_182
